# up-projection k-loops rescheduled like the in-projection loop (SGPR bases + loop-invariant lane offsets, reads done by pair 10, LDS stores behind pairs 10-12, loads two per pair)
# speedup vs baseline: 1.0204x; 1.0019x over previous
; template <bool SWAP, bool SSQ, class AF>
; DI void gemm_main(AF asrc, int m0, const u16* __restrict__ Bw, int ldb, int K, char* smem,
;                   f32x16 (&acc)[4][2], float ssq_eps, float (&rs)[4]) {
;     ...
;   u32x4 ra[8], rb[4];
; #pragma unroll
;   for (int i = 0; i < 4; ++i) rs[i] = 0.f;
; #pragma unroll
;   for (int mi = 0; mi < 4; ++mi)
; #pragma unroll
;     for (int ni = 0; ni < 2; ++ni)
; #pragma unroll
;       for (int i = 0; i < 16; ++i) acc[mi][ni][i] = 0.f;
;   auto gload = [&](int kt) {
;     ASrc s = asrc(kt);
;     const unsigned voffA = (unsigned)(srow * (int)s.ld * 2 + skc * 16);
;     const char* ua = (const char*)s.p + (long)m0 * s.ld * 2;
; #pragma unroll
;     for (int i = 0; i < 8; ++i) ra[i] = *(const u32x4*)(ua + (long)(32 * i) * s.ld * 2 + voffA);
;     const char* ub = (const char*)Bw + (long)kt * 128;
; #pragma unroll
;     for (int i = 0; i < 4; ++i) rb[i] = *(const u32x4*)(ub + (long)(32 * i) * ldb * 2 + voffB);
;   };
;   auto sstore = [&]() {
; #pragma unroll
;     for (int i = 0; i < 8; ++i) *(u32x4*)(sA + lds_st + i * (32 * 144)) = ra[i];
; #pragma unroll
;     for (int i = 0; i < 4; ++i) *(u32x4*)(sB + lds_st + i * (32 * 144)) = rb[i];
;   };
;   const int nkt = K >> 6;
;   const char* pA = sA + (wm * 128 + lr) * 144 + lh * 16;
;   const char* pB = sB + (wn * 64 + lr) * 144 + lh * 16;
;   gload(0);
;   sstore();
;   __syncthreads();
;   for (int kt = 0; kt < nkt; ++kt) {
;     if (kt + 1 < nkt) gload(kt + 1);
;     __builtin_amdgcn_sched_barrier(0);
;     {
;       bf16x8 ar[3], br[2][2];
;       ar[0] = *(const bf16x8*)(pA);
;       ar[1] = *(const bf16x8*)(pA + 32 * 144);
; DI void phase_upproj(const Params& p, const GroupP& g, int l, char* smem, int vb) {
;     ...
;     if (nt < 28) {
;       const bool isq = nt < 12;
;       const int n0 = isq ? nt * 128 : (nt - 12) * 128;
;       const u16* A = isq ? g.cq : g.ckv;
;       const int Kd = isq ? 768 : 512;
;       const u16* Bw = isq ? p.wuqT + (long)l * 1536 * 768 + (long)n0 * 768 : p.wukvT + (long)l * 2048 * 512 + (long)n0 * 512;
;       gemm_main<true, false>([&](int kt) { return ASrc{A + kt * 64, (long)Kd}; }, m0, Bw, Kd, Kd, smem, acc, 0.f, rs);
.LBB0_249:
	s_and_b64 s[6:7], exec, s[90:91]
	s_movk_i32 s6, 0x200
	s_cselect_b32 s87, s6, 0x300
	v_readlane_b32 s6, v254, 36
	v_readlane_b32 s7, v254, 37
	s_load_dwordx16 s[36:51], s[6:7], 0xb8
	s_mul_i32 s6, s18, s11
	v_mov_b32_e32 v7, v200
	s_waitcnt lgkmcnt(0)
	s_cselect_b32 s21, s43, s41
	s_cselect_b32 s92, s42, s40
	s_add_i32 s20, s20, s10
	s_sub_i32 s6, s20, s6
	s_lshl_b32 s88, s6, 8
	v_readfirstlane_b32 s20, v7
	s_mul_hi_i32 s7, s87, s88
	s_mul_i32 s6, s87, s88
	v_ashrrev_i32_e32 v57, 3, v7
	v_lshlrev_b32_e32 v0, 4, v7
	s_lshr_b32 s93, s87, 6
	s_and_b32 s96, s20, 0xfffff80
	s_ashr_i32 s89, s88, 31
	s_lshl_b64 s[6:7], s[6:7], 1
	v_and_b32_e32 v56, 0x70, v0
	v_mul_lo_u32 v0, s87, v57
	s_add_u32 s10, s92, s6
	v_lshl_or_b32 v184, v0, 1, v56
	s_addc_u32 s11, s21, s7
	v_lshl_add_u64 v[0:1], s[10:11], 0, v[184:185]
	s_lshl_b32 s94, s87, 6
	v_lshl_add_u64 v[0:1], v[0:1], 0, s[94:95]
	v_lshl_add_u64 v[2:3], v[0:1], 0, s[94:95]
	global_load_dwordx4 v[8:11], v184, s[10:11]
	global_load_dwordx4 v[12:15], v[0:1], off
	global_load_dwordx4 v[16:19], v[2:3], off
	v_lshl_add_u64 v[0:1], v[2:3], 0, s[94:95]
	v_lshl_add_u64 v[2:3], v[0:1], 0, s[94:95]
	global_load_dwordx4 v[20:23], v[0:1], off
	global_load_dwordx4 v[24:27], v[2:3], off
	v_lshl_add_u64 v[0:1], v[2:3], 0, s[94:95]
	v_lshl_add_u64 v[2:3], v[0:1], 0, s[94:95]
	global_load_dwordx4 v[28:31], v[0:1], off
	global_load_dwordx4 v[32:35], v[2:3], off
	global_load_dwordx4 v[36:39], v184, s[4:5]
	s_add_u32 s6, s4, s94
	s_addc_u32 s7, s5, 0
	global_load_dwordx4 v[40:43], v184, s[6:7]
	s_add_u32 s6, s6, s94
	s_addc_u32 s7, s7, 0
	global_load_dwordx4 v[44:47], v184, s[6:7]
	s_add_u32 s6, s6, s94
	s_addc_u32 s7, s7, 0
	global_load_dwordx4 v[48:51], v184, s[6:7]
	v_lshl_add_u64 v[0:1], v[2:3], 0, s[94:95]
	global_load_dwordx4 v[52:55], v[0:1], off
	v_and_b32_e32 v58, 31, v7
	v_and_or_b32 v59, s20, 64, v58
	s_movk_i32 s20, 0x90
	v_mad_u64_u32 v[138:139], s[6:7], v57, s20, v[56:57]
	v_or_b32_e32 v56, s96, v58
	v_mul_lo_u32 v56, v56, s20
	s_add_i32 s20, s93, -1
	s_add_u32 s92, s4, 0x80
	s_addc_u32 s93, s5, 0
	s_lshl_b32 s4, s87, 7
	s_add_u32 s96, s92, s4
	s_mul_i32 s21, s87, 0xc0
	s_addc_u32 s97, s93, 0
	s_add_u32 vcc_lo, s92, s21
	s_addc_u32 vcc_hi, s93, 0
	s_add_u32 s6, s92, s94
	v_lshrrev_b32_e32 v7, 1, v7
	s_addc_u32 s7, s93, 0
	v_mov_b32_e32 v0, 0
	v_and_b32_e32 v7, 16, v7
	v_mul_u32_u24_e32 v57, 0x90, v59
	s_add_u32 s4, s10, 0x80
	v_mov_b32_e32 v1, v0
	v_mov_b32_e32 v2, v0
	v_mov_b32_e32 v3, v0
	v_mov_b32_e32 v4, v0
	v_mov_b32_e32 v5, v0
	v_mov_b32_e32 v6, v0
	v_add_u32_e32 v140, v57, v7
	v_add_u32_e32 v139, v56, v7
	s_addc_u32 s5, s11, 0
	v_mov_b32_e32 v7, v0
	v_mov_b32_e32 v56, v0
	v_mov_b32_e32 v57, v0
	v_mov_b32_e32 v58, v0
	v_mov_b32_e32 v59, v0
	v_mov_b32_e32 v60, v0
	v_mov_b32_e32 v61, v0
	v_mov_b32_e32 v62, v0
	v_mov_b32_e32 v63, v0
	v_mov_b32_e32 v64, v0
	v_mov_b32_e32 v65, v0
	v_mov_b32_e32 v66, v0
	v_mov_b32_e32 v67, v0
	v_mov_b32_e32 v68, v0
	v_mov_b32_e32 v69, v0
	v_mov_b32_e32 v70, v0
	v_mov_b32_e32 v71, v0
	v_mov_b32_e32 v72, v0
	s_waitcnt vmcnt(4)
	ds_write_b128 v138, v[36:39] offset:36864
	ds_write_b128 v138, v[8:11]
	ds_write_b128 v138, v[12:15] offset:4608
	s_waitcnt vmcnt(3)
	ds_write_b128 v138, v[40:43] offset:41472
	ds_write_b128 v138, v[16:19] offset:9216
	ds_write_b128 v138, v[20:23] offset:13824
	s_waitcnt vmcnt(2)
	ds_write_b128 v138, v[44:47] offset:46080
	ds_write_b128 v138, v[24:27] offset:18432
	ds_write_b128 v138, v[28:31] offset:23040
	s_waitcnt vmcnt(1)
	ds_write_b128 v138, v[48:51] offset:50688
	ds_write_b128 v138, v[32:35] offset:27648
	s_waitcnt vmcnt(0)
	ds_write_b128 v138, v[52:55] offset:32256
	s_waitcnt lgkmcnt(0)
	s_barrier
	v_mov_b32_e32 v8, v0
	v_mov_b32_e32 v9, v0
	v_mov_b32_e32 v10, v0
	v_mov_b32_e32 v11, v0
	v_mov_b32_e32 v12, v0
	v_mov_b32_e32 v13, v0
	v_mov_b32_e32 v14, v0
	v_mov_b32_e32 v15, v0
	v_mov_b32_e32 v16, v0
	v_mov_b32_e32 v17, v0
	v_mov_b32_e32 v18, v0
	v_mov_b32_e32 v19, v0
	v_mov_b32_e32 v20, v0
	v_mov_b32_e32 v21, v0
	v_mov_b32_e32 v22, v0
	v_mov_b32_e32 v23, v0
	v_mov_b32_e32 v24, v0
	v_mov_b32_e32 v25, v0
	v_mov_b32_e32 v26, v0
	v_mov_b32_e32 v27, v0
	v_mov_b32_e32 v28, v0
	v_mov_b32_e32 v29, v0
	v_mov_b32_e32 v30, v0
	v_mov_b32_e32 v31, v0
	v_mov_b32_e32 v32, v0
	v_mov_b32_e32 v33, v0
	v_mov_b32_e32 v34, v0
	v_mov_b32_e32 v35, v0
	v_mov_b32_e32 v36, v0
	v_mov_b32_e32 v37, v0
	v_mov_b32_e32 v38, v0
	v_mov_b32_e32 v39, v0
	v_mov_b32_e32 v40, v0
	v_mov_b32_e32 v41, v0
	v_mov_b32_e32 v42, v0
	v_mov_b32_e32 v43, v0
	v_mov_b32_e32 v44, v0
	v_mov_b32_e32 v45, v0
	v_mov_b32_e32 v46, v0
	v_mov_b32_e32 v47, v0
	v_mov_b32_e32 v48, v0
	v_mov_b32_e32 v49, v0
	v_mov_b32_e32 v50, v0
	v_mov_b32_e32 v51, v0
	v_mov_b32_e32 v52, v0
	v_mov_b32_e32 v53, v0
	v_mov_b32_e32 v54, v0
	v_mov_b32_e32 v55, v0
	v_mov_b32_e32 v73, v0
	v_mov_b32_e32 v74, v0
	v_mov_b32_e32 v75, v0
	v_mov_b32_e32 v76, v0
	v_mov_b32_e32 v77, v0
	v_mov_b32_e32 v78, v0
	v_mov_b32_e32 v79, v0
	v_mov_b32_e32 v80, v0
	v_mov_b32_e32 v81, v0
	v_mov_b32_e32 v82, v0
	v_mov_b32_e32 v83, v0
	v_mov_b32_e32 v84, v0
	v_mov_b32_e32 v85, v0
	v_mov_b32_e32 v86, v0
	v_mov_b32_e32 v87, v0
	v_mov_b32_e32 v88, v0
	v_mov_b32_e32 v89, v0
	v_mov_b32_e32 v90, v0
	v_mov_b32_e32 v91, v0
	v_mov_b32_e32 v92, v0
	v_mov_b32_e32 v93, v0
	v_mov_b32_e32 v94, v0
	v_mov_b32_e32 v95, v0
	v_mov_b32_e32 v96, v0
	v_mov_b32_e32 v97, v0
	v_mov_b32_e32 v98, v0
	v_mov_b32_e32 v99, v0
	v_mov_b32_e32 v100, v0
	v_mov_b32_e32 v101, v0
	v_mov_b32_e32 v102, v0
	v_mov_b32_e32 v103, v0
	v_mov_b32_e32 v104, v0
	v_mov_b32_e32 v105, v0
	v_mov_b32_e32 v106, v0
	v_mov_b32_e32 v107, v0
	v_mov_b32_e32 v108, v0
	v_mov_b32_e32 v109, v0
	v_mov_b32_e32 v110, v0
	v_mov_b32_e32 v111, v0
	v_mov_b32_e32 v112, v0
	v_mov_b32_e32 v113, v0
	v_mov_b32_e32 v114, v0
	v_mov_b32_e32 v115, v0
	v_mov_b32_e32 v116, v0
	v_mov_b32_e32 v117, v0
	v_mov_b32_e32 v118, v0
	v_mov_b32_e32 v119, v0
	v_mov_b32_e32 v120, v0
	v_mov_b32_e32 v121, v0
	v_mov_b32_e32 v122, v0
	v_mov_b32_e32 v123, v0
	v_mov_b32_e32 v124, v0
	v_mov_b32_e32 v125, v0
	v_mov_b32_e32 v126, v0
	v_mov_b32_e32 v127, v0
	v_add_u32_e32 v246, s94, v184
	s_lshl_b64 s[100:101], s[94:95], 2
	v_add_u32_e32 v247, s94, v246
	s_add_u32 s100, s4, s100
	s_addc_u32 s101, s5, s101
	v_add_u32_e32 v248, s94, v247
	ds_read_b128 v[194:197], v140 offset:36864
	ds_read_b128 v[218:221], v140 offset:41472
	ds_read_b128 v[222:225], v139
	ds_read_b128 v[226:229], v139 offset:4608
	ds_read_b128 v[230:233], v139 offset:9216
; #define MFMA(a, b, c) __builtin_amdgcn_mfma_f32_32x32x16_bf16((a), (b), (c), 0, 0, 0)
; template <bool SWAP, bool SSQ, class AF>
; DI void gemm_main(AF asrc, int m0, const u16* __restrict__ Bw, int ldb, int K, char* smem,
;                   f32x16 (&acc)[4][2], float ssq_eps, float (&rs)[4]) {
;     ...
;   for (int kt = 0; kt < nkt; ++kt) {
;     if (kt + 1 < nkt) gload(kt + 1);
;     __builtin_amdgcn_sched_barrier(0);
;     {
;       bf16x8 ar[3], br[2][2];
;       ar[0] = *(const bf16x8*)(pA);
;       ar[1] = *(const bf16x8*)(pA + 32 * 144);
;       br[0][0] = *(const bf16x8*)(pB);
;       br[0][1] = *(const bf16x8*)(pB + 32 * 144);
;       __builtin_amdgcn_sched_group_barrier(0x100, 4, 0);
; #pragma unroll
;       for (int t = 0; t < 16; ++t) {
;         const int ks = t >> 2, mi = t & 3;
;         if (t + 2 < 16) {
;           ar[(t + 2) % 3] = *(const bf16x8*)(pA + ((t + 2) & 3) * (32 * 144) + ((t + 2) >> 2) * 32);
;           if (mi == 1 && ks + 1 < 4) {
;             br[(ks + 1) & 1][0] = *(const bf16x8*)(pB + (ks + 1) * 32);
;             br[(ks + 1) & 1][1] = *(const bf16x8*)(pB + 32 * 144 + (ks + 1) * 32);
;             __builtin_amdgcn_sched_group_barrier(0x100, 3, 0);
;           } else {
;             __builtin_amdgcn_sched_group_barrier(0x100, 1, 0);
;           }
;         }
;         acc[mi][0] = SWAP ? MFMA(br[ks & 1][0], ar[t % 3], acc[mi][0]) : MFMA(ar[t % 3], br[ks & 1][0], acc[mi][0]);
;         acc[mi][1] = SWAP ? MFMA(br[ks & 1][1], ar[t % 3], acc[mi][1]) : MFMA(ar[t % 3], br[ks & 1][1], acc[mi][1]);
;         __builtin_amdgcn_sched_group_barrier(0x008, 2, 0);
;         if (SSQ) {
;           u32x4 u = __builtin_bit_cast(u32x4, ar[t % 3]);
; #pragma unroll
;           for (int j = 0; j < 4; ++j) rs[mi] = dot2bf(u[j], rs[mi]);
;         }
;       }
;     }
;     __syncthreads();
;     if (kt + 1 < nkt) sstore();
;     __syncthreads();
;   }
.LBB0_250:
	ds_read_b128 v[234:237], v139 offset:13824
	global_load_dwordx4 v[144:147], v184, s[4:5]
	global_load_dwordx4 v[148:151], v246, s[4:5]
	s_waitcnt lgkmcnt(3)
	v_mfma_f32_32x32x16_bf16 v[112:127], v[194:197], v[222:225], v[112:127]
	v_mfma_f32_32x32x16_bf16 v[96:111], v[218:221], v[222:225], v[96:111]
	ds_read_b128 v[222:225], v140 offset:36896
	ds_read_b128 v[238:241], v140 offset:41504
	global_load_dwordx4 v[152:155], v247, s[4:5]
	global_load_dwordx4 v[156:159], v248, s[4:5]
	s_waitcnt lgkmcnt(4)
	v_mfma_f32_32x32x16_bf16 v[80:95], v[194:197], v[226:229], v[80:95]
	v_mfma_f32_32x32x16_bf16 v[64:79], v[218:221], v[226:229], v[64:79]
	ds_read_b128 v[226:229], v139 offset:32
	global_load_dwordx4 v[160:163], v184, s[100:101]
	global_load_dwordx4 v[164:167], v246, s[100:101]
	s_waitcnt lgkmcnt(4)
	v_mfma_f32_32x32x16_bf16 v[48:63], v[194:197], v[230:233], v[48:63]
	v_mfma_f32_32x32x16_bf16 v[32:47], v[218:221], v[230:233], v[32:47]
	ds_read_b128 v[230:233], v139 offset:4640
	global_load_dwordx4 v[168:171], v247, s[100:101]
	global_load_dwordx4 v[172:175], v248, s[100:101]
	s_waitcnt lgkmcnt(4)
	v_mfma_f32_32x32x16_bf16 v[16:31], v[194:197], v[234:237], v[16:31]
	v_mfma_f32_32x32x16_bf16 v[0:15], v[218:221], v[234:237], v[0:15]
	ds_read_b128 v[194:197], v139 offset:9248
	ds_read_b128 v[218:221], v139 offset:13856
	global_load_dwordx4 v[176:179], v184, s[92:93]
	global_load_dwordx4 v[180:183], v184, s[6:7]
	s_waitcnt lgkmcnt(3)
	v_mfma_f32_32x32x16_bf16 v[112:127], v[222:225], v[226:229], v[112:127]
	v_mfma_f32_32x32x16_bf16 v[96:111], v[238:241], v[226:229], v[96:111]
	ds_read_b128 v[226:229], v140 offset:36928
	ds_read_b128 v[202:205], v140 offset:41536
	global_load_dwordx4 v[186:189], v184, s[96:97]
	global_load_dwordx4 v[190:193], v184, vcc
	s_waitcnt lgkmcnt(4)
	v_mfma_f32_32x32x16_bf16 v[80:95], v[222:225], v[230:233], v[80:95]
	v_mfma_f32_32x32x16_bf16 v[64:79], v[238:241], v[230:233], v[64:79]
	ds_read_b128 v[230:233], v139 offset:64
	ds_read_b128 v[206:209], v139 offset:4672
	s_waitcnt lgkmcnt(5)
	v_mfma_f32_32x32x16_bf16 v[48:63], v[222:225], v[194:197], v[48:63]
	v_mfma_f32_32x32x16_bf16 v[32:47], v[238:241], v[194:197], v[32:47]
	ds_read_b128 v[194:197], v139 offset:9280
	s_waitcnt lgkmcnt(5)
	v_mfma_f32_32x32x16_bf16 v[16:31], v[222:225], v[218:221], v[16:31]
	v_mfma_f32_32x32x16_bf16 v[0:15], v[238:241], v[218:221], v[0:15]
	ds_read_b128 v[222:225], v139 offset:13888
	ds_read_b128 v[242:245], v140 offset:36960
	ds_read_b128 v[234:237], v140 offset:41568
	s_waitcnt lgkmcnt(5)
	v_mfma_f32_32x32x16_bf16 v[112:127], v[226:229], v[230:233], v[112:127]
	v_mfma_f32_32x32x16_bf16 v[96:111], v[202:205], v[230:233], v[96:111]
	ds_read_b128 v[218:221], v139 offset:96
	ds_read_b128 v[230:233], v139 offset:4704
	s_waitcnt lgkmcnt(6)
	v_mfma_f32_32x32x16_bf16 v[80:95], v[226:229], v[206:209], v[80:95]
	v_mfma_f32_32x32x16_bf16 v[64:79], v[202:205], v[206:209], v[64:79]
	ds_read_b128 v[238:241], v139 offset:9312
	ds_read_b128 v[206:209], v139 offset:13920
	s_waitcnt lgkmcnt(0)
	s_barrier
	v_mfma_f32_32x32x16_bf16 v[48:63], v[226:229], v[194:197], v[48:63]
	v_mfma_f32_32x32x16_bf16 v[32:47], v[202:205], v[194:197], v[32:47]
	s_waitcnt vmcnt(11)
	ds_write_b128 v138, v[144:147]
	s_waitcnt vmcnt(10)
	ds_write_b128 v138, v[148:151] offset:4608
	s_waitcnt vmcnt(9)
	ds_write_b128 v138, v[152:155] offset:9216
	s_waitcnt vmcnt(8)
	ds_write_b128 v138, v[156:159] offset:13824
	v_mfma_f32_32x32x16_bf16 v[16:31], v[226:229], v[222:225], v[16:31]
	v_mfma_f32_32x32x16_bf16 v[0:15], v[202:205], v[222:225], v[0:15]
	s_waitcnt vmcnt(7)
	ds_write_b128 v138, v[160:163] offset:18432
	s_waitcnt vmcnt(6)
	ds_write_b128 v138, v[164:167] offset:23040
	s_waitcnt vmcnt(5)
	ds_write_b128 v138, v[168:171] offset:27648
	s_waitcnt vmcnt(4)
	ds_write_b128 v138, v[172:175] offset:32256
	v_mfma_f32_32x32x16_bf16 v[112:127], v[242:245], v[218:221], v[112:127]
	v_mfma_f32_32x32x16_bf16 v[96:111], v[234:237], v[218:221], v[96:111]
	s_waitcnt vmcnt(3)
	ds_write_b128 v138, v[176:179] offset:36864
	s_waitcnt vmcnt(2)
	ds_write_b128 v138, v[180:183] offset:41472
	s_waitcnt vmcnt(1)
	ds_write_b128 v138, v[186:189] offset:46080
	s_waitcnt vmcnt(0)
	ds_write_b128 v138, v[190:193] offset:50688
	v_mfma_f32_32x32x16_bf16 v[80:95], v[242:245], v[230:233], v[80:95]
	v_mfma_f32_32x32x16_bf16 v[64:79], v[234:237], v[230:233], v[64:79]
	s_waitcnt lgkmcnt(0)
	s_barrier
	ds_read_b128 v[194:197], v140 offset:36864
	ds_read_b128 v[218:221], v140 offset:41472
	ds_read_b128 v[222:225], v139
	ds_read_b128 v[226:229], v139 offset:4608
	ds_read_b128 v[230:233], v139 offset:9216
	v_mfma_f32_32x32x16_bf16 v[48:63], v[242:245], v[238:241], v[48:63]
	v_mfma_f32_32x32x16_bf16 v[32:47], v[234:237], v[238:241], v[32:47]
	v_mfma_f32_32x32x16_bf16 v[16:31], v[242:245], v[206:209], v[16:31]
	v_mfma_f32_32x32x16_bf16 v[0:15], v[234:237], v[206:209], v[0:15]
	s_add_u32 s92, s92, 0x80
	s_addc_u32 s93, s93, 0
	s_add_u32 s96, s96, 0x80
	s_addc_u32 s97, s97, 0
	s_add_u32 vcc_lo, vcc_lo, 0x80
	s_addc_u32 vcc_hi, vcc_hi, 0
	s_add_u32 s6, s6, 0x80
	s_addc_u32 s7, s7, 0
	s_add_u32 s4, s4, 0x80
	s_addc_u32 s5, s5, 0
	s_add_u32 s100, s100, 0x80
	s_addc_u32 s101, s101, 0
	s_add_i32 s20, s20, -1
	s_cmp_lg_u32 s20, 0
	s_cbranch_scc1 .LBB0_250
; #define MFMA(a, b, c) __builtin_amdgcn_mfma_f32_32x32x16_bf16((a), (b), (c), 0, 0, 0)
; template <bool SWAP, bool SSQ, class AF>
; DI void gemm_main(AF asrc, int m0, const u16* __restrict__ Bw, int ldb, int K, char* smem,
;                   f32x16 (&acc)[4][2], float ssq_eps, float (&rs)[4]) {
;     ...
;   for (int kt = 0; kt < nkt; ++kt) {
;     if (kt + 1 < nkt) gload(kt + 1);
;     __builtin_amdgcn_sched_barrier(0);
;     {
;       bf16x8 ar[3], br[2][2];
;       ar[0] = *(const bf16x8*)(pA);
;       ar[1] = *(const bf16x8*)(pA + 32 * 144);
;       br[0][0] = *(const bf16x8*)(pB);
;       br[0][1] = *(const bf16x8*)(pB + 32 * 144);
;       __builtin_amdgcn_sched_group_barrier(0x100, 4, 0);
; #pragma unroll
;       for (int t = 0; t < 16; ++t) {
;         const int ks = t >> 2, mi = t & 3;
;         if (t + 2 < 16) {
;           ar[(t + 2) % 3] = *(const bf16x8*)(pA + ((t + 2) & 3) * (32 * 144) + ((t + 2) >> 2) * 32);
;           if (mi == 1 && ks + 1 < 4) {
;             br[(ks + 1) & 1][0] = *(const bf16x8*)(pB + (ks + 1) * 32);
;             br[(ks + 1) & 1][1] = *(const bf16x8*)(pB + 32 * 144 + (ks + 1) * 32);
;             __builtin_amdgcn_sched_group_barrier(0x100, 3, 0);
;           } else {
;             __builtin_amdgcn_sched_group_barrier(0x100, 1, 0);
;           }
;         }
;         acc[mi][0] = SWAP ? MFMA(br[ks & 1][0], ar[t % 3], acc[mi][0]) : MFMA(ar[t % 3], br[ks & 1][0], acc[mi][0]);
;         acc[mi][1] = SWAP ? MFMA(br[ks & 1][1], ar[t % 3], acc[mi][1]) : MFMA(ar[t % 3], br[ks & 1][1], acc[mi][1]);
;         __builtin_amdgcn_sched_group_barrier(0x008, 2, 0);
;         if (SSQ) {
;           u32x4 u = __builtin_bit_cast(u32x4, ar[t % 3]);
; #pragma unroll
;           for (int j = 0; j < 4; ++j) rs[mi] = dot2bf(u[j], rs[mi]);
;         }
;       }
;     }
;     __syncthreads();
;     if (kt + 1 < nkt) sstore();
;     __syncthreads();
;   }
; DI void phase_upproj(const Params& p, const GroupP& g, int l, char* smem, int vb) {
;     ...
;       {
;         const float* sq = p.rowsq + (size_t)(l * 2 + (isq ? 0 : 1)) * 50432 + g.seq0 + m0 + wm * 128 + lr;
;         const float invK = 1.f / (float)Kd;
; #pragma unroll
;         for (int mi = 0; mi < 4; ++mi) rs[mi] = __builtin_amdgcn_rsqf(sq[mi * 32] * invK + 1e-6f);
;       }
	ds_read_b128 v[144:147], v140 offset:36864
	ds_read_b128 v[156:159], v140 offset:41472
	ds_read_b128 v[148:151], v139
	ds_read_b128 v[152:155], v139 offset:4608
	ds_read_b128 v[160:163], v139 offset:9216
	v_cndmask_b32_e64 v138, 0, 1, s[90:91]
	v_readlane_b32 s5, v253, 7
	v_readfirstlane_b32 s4, v138
	s_or_b32 s4, s23, s4
	s_waitcnt lgkmcnt(2)
	v_mfma_f32_32x32x16_bf16 v[112:127], v[144:147], v[148:151], v[112:127]
	s_mul_i32 s4, s4, 0x31400
	s_add_u32 s6, s5, s4
	v_readlane_b32 s4, v254, 41
	s_addc_u32 s7, s4, 0
	s_lshl_b64 s[4:5], s[88:89], 2
	s_add_u32 s4, s6, s4
	s_addc_u32 s5, s7, s5
	v_mfma_f32_32x32x16_bf16 v[96:111], v[156:159], v[148:151], v[96:111]
	ds_read_b128 v[164:167], v140 offset:36896
	ds_read_b128 v[168:171], v140 offset:41504
	ds_read_b128 v[148:151], v139 offset:13824
	s_add_u32 s4, s4, s12
	s_addc_u32 s5, s5, s13
	v_cvt_f32_u32_e32 v142, s87
	v_readlane_b32 s6, v254, 36
	s_waitcnt lgkmcnt(4)
	v_mfma_f32_32x32x16_bf16 v[80:95], v[144:147], v[152:155], v[80:95]
	s_mov_b32 s87, s22
	v_readlane_b32 s7, v254, 37
	v_mfma_f32_32x32x16_bf16 v[64:79], v[156:159], v[152:155], v[64:79]
	ds_read_b128 v[152:155], v139 offset:32
	s_waitcnt lgkmcnt(4)
	v_mfma_f32_32x32x16_bf16 v[48:63], v[144:147], v[160:163], v[48:63]
	v_mfma_f32_32x32x16_bf16 v[32:47], v[156:159], v[160:163], v[32:47]
	ds_read_b128 v[160:163], v139 offset:4640
	s_waitcnt lgkmcnt(2)
	v_mfma_f32_32x32x16_bf16 v[16:31], v[144:147], v[148:151], v[16:31]
	v_mfma_f32_32x32x16_bf16 v[0:15], v[156:159], v[148:151], v[0:15]
	ds_read_b128 v[144:147], v139 offset:9248
	s_waitcnt lgkmcnt(2)
	v_mfma_f32_32x32x16_bf16 v[112:127], v[164:167], v[152:155], v[112:127]
	v_mfma_f32_32x32x16_bf16 v[96:111], v[168:171], v[152:155], v[96:111]
	ds_read_b128 v[152:155], v140 offset:36928
	ds_read_b128 v[156:159], v140 offset:41536
	ds_read_b128 v[148:151], v139 offset:13856
	s_waitcnt lgkmcnt(4)
	v_mfma_f32_32x32x16_bf16 v[80:95], v[164:167], v[160:163], v[80:95]
	v_mfma_f32_32x32x16_bf16 v[64:79], v[168:171], v[160:163], v[64:79]
	ds_read_b128 v[160:163], v139 offset:64
	s_waitcnt lgkmcnt(4)
	v_mfma_f32_32x32x16_bf16 v[48:63], v[164:167], v[144:147], v[48:63]
	v_mfma_f32_32x32x16_bf16 v[32:47], v[168:171], v[144:147], v[32:47]
	ds_read_b128 v[144:147], v139 offset:4672
	s_waitcnt lgkmcnt(2)
	v_mfma_f32_32x32x16_bf16 v[16:31], v[164:167], v[148:151], v[16:31]
	v_mfma_f32_32x32x16_bf16 v[0:15], v[168:171], v[148:151], v[0:15]
	ds_read_b128 v[148:151], v139 offset:9280
	s_waitcnt lgkmcnt(2)
	v_mfma_f32_32x32x16_bf16 v[112:127], v[152:155], v[160:163], v[112:127]
	v_mfma_f32_32x32x16_bf16 v[96:111], v[156:159], v[160:163], v[96:111]
	ds_read_b128 v[164:167], v140 offset:36960
	ds_read_b128 v[168:171], v140 offset:41568
	ds_read_b128 v[160:163], v139 offset:13888
	s_waitcnt lgkmcnt(4)
	v_mfma_f32_32x32x16_bf16 v[80:95], v[152:155], v[144:147], v[80:95]
	v_mfma_f32_32x32x16_bf16 v[64:79], v[156:159], v[144:147], v[64:79]
	ds_read_b128 v[144:147], v139 offset:96
	s_waitcnt lgkmcnt(4)
	v_mfma_f32_32x32x16_bf16 v[48:63], v[152:155], v[148:151], v[48:63]
	v_mfma_f32_32x32x16_bf16 v[32:47], v[156:159], v[148:151], v[32:47]
	ds_read_b128 v[148:151], v139 offset:4704
	s_waitcnt lgkmcnt(2)
	v_mfma_f32_32x32x16_bf16 v[16:31], v[152:155], v[160:163], v[16:31]
	v_mfma_f32_32x32x16_bf16 v[0:15], v[156:159], v[160:163], v[0:15]
	ds_read_b128 v[152:155], v139 offset:9312
	s_waitcnt lgkmcnt(2)
	v_mfma_f32_32x32x16_bf16 v[112:127], v[164:167], v[144:147], v[112:127]
	v_mfma_f32_32x32x16_bf16 v[96:111], v[168:171], v[144:147], v[96:111]
	ds_read_b128 v[144:147], v139 offset:13920
	s_waitcnt lgkmcnt(0)
	s_barrier
	s_barrier
; DI void phase_upproj(const Params& p, const GroupP& g, int l, char* smem, int vb) {
;     ...
;       {
;         const float* sq = p.rowsq + (size_t)(l * 2 + (isq ? 0 : 1)) * 50432 + g.seq0 + m0 + wm * 128 + lr;
;         const float invK = 1.f / (float)Kd;
; #pragma unroll
;         for (int mi = 0; mi < 4; ++mi) rs[mi] = __builtin_amdgcn_rsqf(sq[mi * 32] * invK + 1e-6f);
;       }
;       const int nw0 = n0 + wn * 64;
;       if (isq) {
;         const int head = nw0 / 192, w = nw0 - head * 192;
; #pragma unroll
;         for (int mi = 0; mi < 4; ++mi) {
;           int m = m0 + wm * 128 + mi * 32 + lr;
;           float r = rs[mi];
;           if (w == 128) {
;             int b = m / g.Lp, t = m - b * g.Lp;
;             f32x16 a0 = acc[mi][0], a1 = acc[mi][1];
; #pragma unroll
;             for (int i = 0; i < 16; ++i) { a0[i] *= r; a1[i] *= r; }
;             rope_store(a0, a1, p.rope + t * 32, g.q + (long)m * 1536 + nw0, lh);
;           } else {
;             u16* qp = g.q + (long)m * 1536 + nw0;
; #pragma unroll
;             for (int ni = 0; ni < 2; ++ni)
; #pragma unroll
;               for (int pr = 0; pr < 2; ++pr)
;                 store_bf8_pair(qp + ni * 32 + 16 * pr, lh, acc[mi][ni][8 * pr] * r, acc[mi][ni][8 * pr + 1] * r,
;                                acc[mi][ni][8 * pr + 2] * r, acc[mi][ni][8 * pr + 3] * r, acc[mi][ni][8 * pr + 4] * r,
;                                acc[mi][ni][8 * pr + 5] * r, acc[mi][ni][8 * pr + 6] * r, acc[mi][ni][8 * pr + 7] * r);
	global_load_dword v138, v143, s[4:5]
	global_load_dword v139, v143, s[4:5] offset:128
	global_load_dword v140, v143, s[4:5] offset:256
	v_mfma_f32_32x32x16_bf16 v[80:95], v[164:167], v[148:151], v[80:95]
	v_mfma_f32_32x32x16_bf16 v[64:79], v[168:171], v[148:151], v[64:79]
	global_load_dword v148, v143, s[4:5] offset:384
	v_div_scale_f32 v149, s[4:5], v142, v142, 1.0
	v_rcp_f32_e32 v150, v149
	s_mov_b64 s[4:5], -1
	v_mfma_f32_32x32x16_bf16 v[48:63], v[164:167], v[152:155], v[48:63]
	v_mfma_f32_32x32x16_bf16 v[32:47], v[168:171], v[152:155], v[32:47]
	v_mfma_f32_32x32x16_bf16 v[16:31], v[164:167], v[144:147], v[16:31]
	v_mfma_f32_32x32x16_bf16 v[0:15], v[168:171], v[144:147], v[0:15]
	v_fma_f32 v144, -v149, v150, 1.0
	v_fmac_f32_e32 v150, v144, v150
	v_div_scale_f32 v144, vcc, 1.0, v142, 1.0
	v_mul_f32_e32 v145, v144, v150
	v_fma_f32 v146, -v149, v145, v144
	v_fmac_f32_e32 v145, v146, v150
	v_fma_f32 v144, -v149, v145, v144
	v_div_fmas_f32 v144, v144, v150, v145
	v_div_fixup_f32 v145, v144, v142, 1.0
	v_add_u32_e32 v146, s88, v129
	s_andn2_b64 vcc, exec, s[8:9]
	s_waitcnt vmcnt(3)
	v_fmaak_f32 v138, v145, v138, 0x358637bd
	v_rsq_f32_e32 v144, v138
	s_waitcnt vmcnt(2)
	v_fmaak_f32 v138, v145, v139, 0x358637bd
	v_rsq_f32_e32 v142, v138
	s_waitcnt vmcnt(1)
	v_fmaak_f32 v138, v145, v140, 0x358637bd
	v_rsq_f32_e32 v140, v138
	s_waitcnt vmcnt(0)
	v_fmaak_f32 v138, v145, v148, 0x358637bd
	v_rsq_f32_e32 v138, v138
	s_cbranch_vccnz .LBB0_264
	s_or_b32 s88, s19, s15
	s_mul_hi_i32 s4, s88, 0x2aaaaaab
	s_lshr_b32 s5, s4, 31
	s_lshr_b32 s4, s4, 5
	s_add_i32 s4, s4, s5
	s_mulk_i32 s4, 0xc0
	s_sub_i32 s4, s88, s4
	s_cmpk_lg_i32 s4, 0x80
	s_cselect_b64 s[4:5], -1, 0
	s_ashr_i32 s89, s88, 31
	s_mov_b64 s[6:7], -1
	s_and_b64 vcc, exec, s[4:5]
	v_lshlrev_b32_e32 v184, 1, v130
	s_cbranch_vccz .LBB0_254
	v_readlane_b32 s6, v254, 36
	v_readlane_b32 s7, v254, 37
	s_load_dwordx16 s[36:51], s[6:7], 0xf8
	s_movk_i32 s6, 0xc00
	v_pk_mul_f32 v[150:151], v[114:115], v[144:145] op_sel_hi:[1,0]
	v_pk_mul_f32 v[154:155], v[116:117], v[144:145] op_sel_hi:[1,0]
	v_pk_mul_f32 v[156:157], v[118:119], v[144:145] op_sel_hi:[1,0]
	s_waitcnt lgkmcnt(0)
	v_mov_b64_e32 v[148:149], s[38:39]
	v_mad_i64_i32 v[148:149], s[6:7], v146, s6, v[148:149]
	v_lshl_add_u64 v[148:149], s[88:89], 1, v[148:149]
	v_lshl_add_u64 v[152:153], v[148:149], 0, v[184:185]
	v_pk_mul_f32 v[148:149], v[112:113], v[144:145] op_sel_hi:[1,0]
	s_mov_b64 s[6:7], 0
	v_cvt_pk_bf16_f32 v148, v148, v149
	v_cvt_pk_bf16_f32 v149, v150, v151
	v_cvt_pk_bf16_f32 v150, v154, v155
	v_cvt_pk_bf16_f32 v151, v156, v157
	s_nop 0
	v_permlane32_swap_b32_e32 v148, v150
	v_permlane32_swap_b32_e32 v149, v151
	global_store_dwordx4 v[152:153], v[148:151], off
	v_pk_mul_f32 v[154:155], v[124:125], v[144:145] op_sel_hi:[1,0]
	v_pk_mul_f32 v[156:157], v[126:127], v[144:145] op_sel_hi:[1,0]
	v_pk_mul_f32 v[148:149], v[120:121], v[144:145] op_sel_hi:[1,0]
	v_pk_mul_f32 v[150:151], v[122:123], v[144:145] op_sel_hi:[1,0]
	v_cvt_pk_bf16_f32 v148, v148, v149
	v_cvt_pk_bf16_f32 v149, v150, v151
	v_cvt_pk_bf16_f32 v150, v154, v155
	v_cvt_pk_bf16_f32 v151, v156, v157
	s_nop 0
	v_permlane32_swap_b32_e32 v148, v150
	v_permlane32_swap_b32_e32 v149, v151
	global_store_dwordx4 v[152:153], v[148:151], off offset:32
	v_pk_mul_f32 v[154:155], v[100:101], v[144:145] op_sel_hi:[1,0]
	v_pk_mul_f32 v[156:157], v[102:103], v[144:145] op_sel_hi:[1,0]
	v_pk_mul_f32 v[148:149], v[96:97], v[144:145] op_sel_hi:[1,0]
	v_pk_mul_f32 v[150:151], v[98:99], v[144:145] op_sel_hi:[1,0]
	v_cvt_pk_bf16_f32 v148, v148, v149
	v_cvt_pk_bf16_f32 v149, v150, v151
	v_cvt_pk_bf16_f32 v150, v154, v155
	v_cvt_pk_bf16_f32 v151, v156, v157
	s_nop 0
	v_permlane32_swap_b32_e32 v148, v150
	v_permlane32_swap_b32_e32 v149, v151
	global_store_dwordx4 v[152:153], v[148:151], off offset:64
	v_pk_mul_f32 v[154:155], v[108:109], v[144:145] op_sel_hi:[1,0]
	v_pk_mul_f32 v[156:157], v[110:111], v[144:145] op_sel_hi:[1,0]
	v_pk_mul_f32 v[148:149], v[104:105], v[144:145] op_sel_hi:[1,0]
	v_pk_mul_f32 v[150:151], v[106:107], v[144:145] op_sel_hi:[1,0]
	v_cvt_pk_bf16_f32 v148, v148, v149
	v_cvt_pk_bf16_f32 v149, v150, v151
	v_cvt_pk_bf16_f32 v150, v154, v155
	v_cvt_pk_bf16_f32 v151, v156, v157
	s_nop 0
	v_permlane32_swap_b32_e32 v148, v150
	v_permlane32_swap_b32_e32 v149, v151
	global_store_dwordx4 v[152:153], v[148:151], off offset:96

; template <bool SWAP, bool SSQ, class AF>
; DI void gemm_main(AF asrc, int m0, const u16* __restrict__ Bw, int ldb, int K, char* smem,
;                   f32x16 (&acc)[4][2], float ssq_eps, float (&rs)[4]) {
;     ...
;   u32x4 ra[8], rb[4];
; #pragma unroll
;   for (int i = 0; i < 4; ++i) rs[i] = 0.f;
; #pragma unroll
;   for (int mi = 0; mi < 4; ++mi)
; #pragma unroll
;     for (int ni = 0; ni < 2; ++ni)
; #pragma unroll
;       for (int i = 0; i < 16; ++i) acc[mi][ni][i] = 0.f;
;   auto gload = [&](int kt) {
;     ASrc s = asrc(kt);
;     const unsigned voffA = (unsigned)(srow * (int)s.ld * 2 + skc * 16);
;     const char* ua = (const char*)s.p + (long)m0 * s.ld * 2;
; #pragma unroll
;     for (int i = 0; i < 8; ++i) ra[i] = *(const u32x4*)(ua + (long)(32 * i) * s.ld * 2 + voffA);
;     const char* ub = (const char*)Bw + (long)kt * 128;
; #pragma unroll
;     for (int i = 0; i < 4; ++i) rb[i] = *(const u32x4*)(ub + (long)(32 * i) * ldb * 2 + voffB);
;   };
;   auto sstore = [&]() {
; #pragma unroll
;     for (int i = 0; i < 8; ++i) *(u32x4*)(sA + lds_st + i * (32 * 144)) = ra[i];
; #pragma unroll
;     for (int i = 0; i < 4; ++i) *(u32x4*)(sB + lds_st + i * (32 * 144)) = rb[i];
;   };
;   const int nkt = K >> 6;
;   const char* pA = sA + (wm * 128 + lr) * 144 + lh * 16;
;   const char* pB = sB + (wn * 64 + lr) * 144 + lh * 16;
;   gload(0);
;   sstore();
;   __syncthreads();
;   for (int kt = 0; kt < nkt; ++kt) {
;     if (kt + 1 < nkt) gload(kt + 1);
;     __builtin_amdgcn_sched_barrier(0);
;     {
;       bf16x8 ar[3], br[2][2];
;       ar[0] = *(const bf16x8*)(pA);
;       ar[1] = *(const bf16x8*)(pA + 32 * 144);
; DI void phase_upproj(const Params& p, const GroupP& g, int l, char* smem, int vb) {
;     ...
;     if (nt < 28) {
;       const bool isq = nt < 12;
;       const int n0 = isq ? nt * 128 : (nt - 12) * 128;
;       const u16* A = isq ? g.cq : g.ckv;
;       const int Kd = isq ? 768 : 512;
;       const u16* Bw = isq ? p.wuqT + (long)l * 1536 * 768 + (long)n0 * 768 : p.wukvT + (long)l * 2048 * 512 + (long)n0 * 512;
;       gemm_main<true, false>([&](int kt) { return ASrc{A + kt * 64, (long)Kd}; }, m0, Bw, Kd, Kd, smem, acc, 0.f, rs);
.LBB0_353:
	s_and_b64 s[6:7], exec, s[92:93]
	s_movk_i32 s6, 0x200
	s_cselect_b32 s21, s6, 0x300
	v_readlane_b32 s6, v254, 36
	v_readlane_b32 s7, v254, 37
	s_load_dwordx16 s[44:59], s[6:7], 0x28
	s_mul_i32 s6, s43, s11
	v_mov_b32_e32 v7, v200
	s_waitcnt lgkmcnt(0)
	s_cselect_b32 s87, s51, s49
	s_cselect_b32 s89, s50, s48
	s_add_i32 s86, s86, s10
	s_sub_i32 s6, s86, s6
	s_lshl_b32 s90, s6, 8
	v_readfirstlane_b32 s86, v7
	s_mul_hi_i32 s7, s21, s90
	s_mul_i32 s6, s21, s90
	v_ashrrev_i32_e32 v57, 3, v7
	v_lshlrev_b32_e32 v0, 4, v7
	s_lshr_b32 s96, s21, 6
	s_and_b32 s97, s86, 0xfffff80
	s_ashr_i32 s91, s90, 31
	s_lshl_b64 s[6:7], s[6:7], 1
	v_and_b32_e32 v56, 0x70, v0
	v_mul_lo_u32 v0, s21, v57
	s_add_u32 s6, s89, s6
	v_lshl_or_b32 v184, v0, 1, v56
	s_addc_u32 s7, s87, s7
	v_lshl_add_u64 v[0:1], s[6:7], 0, v[184:185]
	s_lshl_b32 s94, s21, 6
	v_lshl_add_u64 v[0:1], v[0:1], 0, s[94:95]
	v_lshl_add_u64 v[2:3], v[0:1], 0, s[94:95]
	global_load_dwordx4 v[8:11], v184, s[6:7]
	global_load_dwordx4 v[12:15], v[0:1], off
	global_load_dwordx4 v[16:19], v[2:3], off
	v_lshl_add_u64 v[0:1], v[2:3], 0, s[94:95]
	v_lshl_add_u64 v[2:3], v[0:1], 0, s[94:95]
	global_load_dwordx4 v[20:23], v[0:1], off
	global_load_dwordx4 v[24:27], v[2:3], off
	v_lshl_add_u64 v[0:1], v[2:3], 0, s[94:95]
	v_lshl_add_u64 v[2:3], v[0:1], 0, s[94:95]
	global_load_dwordx4 v[28:31], v[0:1], off
	global_load_dwordx4 v[32:35], v[2:3], off
	global_load_dwordx4 v[36:39], v184, s[4:5]
	s_add_u32 s10, s4, s94
	s_addc_u32 s11, s5, 0
	global_load_dwordx4 v[40:43], v184, s[10:11]
	s_add_u32 s10, s10, s94
	s_addc_u32 s11, s11, 0
	global_load_dwordx4 v[44:47], v184, s[10:11]
	s_add_u32 s10, s10, s94
	s_addc_u32 s11, s11, 0
	global_load_dwordx4 v[48:51], v184, s[10:11]
	v_lshl_add_u64 v[0:1], v[2:3], 0, s[94:95]
	global_load_dwordx4 v[52:55], v[0:1], off
	v_and_b32_e32 v58, 31, v7
	s_add_i32 s89, s96, -1
	v_and_or_b32 v59, s86, 64, v58
	s_movk_i32 s86, 0x90
	s_add_u32 s96, s4, 0x80
	v_mad_u64_u32 v[138:139], s[10:11], v57, s86, v[56:57]
	v_or_b32_e32 v56, s97, v58
	s_addc_u32 s97, s5, 0
	s_lshl_b32 s4, s21, 7
	s_add_u32 vcc_lo, s96, s4
	s_mul_i32 s87, s21, 0xc0
	s_addc_u32 vcc_hi, s97, 0
	s_add_u32 s10, s96, s87
	s_addc_u32 s11, s97, 0
	v_mul_lo_u32 v56, v56, s86
	s_add_u32 s86, s96, s94
	v_lshrrev_b32_e32 v7, 1, v7
	s_addc_u32 s87, s97, 0
	v_mov_b32_e32 v0, 0
	v_and_b32_e32 v7, 16, v7
	v_mul_u32_u24_e32 v57, 0x90, v59
	s_add_u32 s4, s6, 0x80
	v_mov_b32_e32 v1, v0
	v_mov_b32_e32 v2, v0
	v_mov_b32_e32 v3, v0
	v_mov_b32_e32 v4, v0
	v_mov_b32_e32 v5, v0
	v_mov_b32_e32 v6, v0
	v_add_u32_e32 v140, v57, v7
	v_add_u32_e32 v139, v56, v7
	s_addc_u32 s5, s7, 0
	v_mov_b32_e32 v7, v0
	v_mov_b32_e32 v56, v0
	v_mov_b32_e32 v57, v0
	v_mov_b32_e32 v58, v0
	v_mov_b32_e32 v59, v0
	v_mov_b32_e32 v60, v0
	v_mov_b32_e32 v61, v0
	v_mov_b32_e32 v62, v0
	v_mov_b32_e32 v63, v0
	v_mov_b32_e32 v64, v0
	v_mov_b32_e32 v65, v0
	v_mov_b32_e32 v66, v0
	v_mov_b32_e32 v67, v0
	v_mov_b32_e32 v68, v0
	v_mov_b32_e32 v69, v0
	v_mov_b32_e32 v70, v0
	v_mov_b32_e32 v71, v0
	v_mov_b32_e32 v72, v0
	s_waitcnt vmcnt(4)
	ds_write_b128 v138, v[36:39] offset:36864
	ds_write_b128 v138, v[8:11]
	ds_write_b128 v138, v[12:15] offset:4608
	s_waitcnt vmcnt(3)
	ds_write_b128 v138, v[40:43] offset:41472
	ds_write_b128 v138, v[16:19] offset:9216
	ds_write_b128 v138, v[20:23] offset:13824
	s_waitcnt vmcnt(2)
	ds_write_b128 v138, v[44:47] offset:46080
	ds_write_b128 v138, v[24:27] offset:18432
	ds_write_b128 v138, v[28:31] offset:23040
	s_waitcnt vmcnt(1)
	ds_write_b128 v138, v[48:51] offset:50688
	ds_write_b128 v138, v[32:35] offset:27648
	s_waitcnt vmcnt(0)
	ds_write_b128 v138, v[52:55] offset:32256
	v_mov_b32_e32 v8, v0
	v_mov_b32_e32 v9, v0
	v_mov_b32_e32 v10, v0
	v_mov_b32_e32 v11, v0
	v_mov_b32_e32 v12, v0
	v_mov_b32_e32 v13, v0
	v_mov_b32_e32 v14, v0
	v_mov_b32_e32 v15, v0
	v_mov_b32_e32 v16, v0
	v_mov_b32_e32 v17, v0
	v_mov_b32_e32 v18, v0
	v_mov_b32_e32 v19, v0
	v_mov_b32_e32 v20, v0
	v_mov_b32_e32 v21, v0
	v_mov_b32_e32 v22, v0
	v_mov_b32_e32 v23, v0
	v_mov_b32_e32 v24, v0
	v_mov_b32_e32 v25, v0
	v_mov_b32_e32 v26, v0
	v_mov_b32_e32 v27, v0
	v_mov_b32_e32 v28, v0
	v_mov_b32_e32 v29, v0
	v_mov_b32_e32 v30, v0
	v_mov_b32_e32 v31, v0
	v_mov_b32_e32 v32, v0
	v_mov_b32_e32 v33, v0
	v_mov_b32_e32 v34, v0
	v_mov_b32_e32 v35, v0
	v_mov_b32_e32 v36, v0
	v_mov_b32_e32 v37, v0
	v_mov_b32_e32 v38, v0
	v_mov_b32_e32 v39, v0
	v_mov_b32_e32 v40, v0
	v_mov_b32_e32 v41, v0
	v_mov_b32_e32 v42, v0
	v_mov_b32_e32 v43, v0
	v_mov_b32_e32 v44, v0
	v_mov_b32_e32 v45, v0
	v_mov_b32_e32 v46, v0
	v_mov_b32_e32 v47, v0
	v_mov_b32_e32 v48, v0
	v_mov_b32_e32 v49, v0
	v_mov_b32_e32 v50, v0
	v_mov_b32_e32 v51, v0
	v_mov_b32_e32 v52, v0
	v_mov_b32_e32 v53, v0
	v_mov_b32_e32 v54, v0
	v_mov_b32_e32 v55, v0
	v_mov_b32_e32 v73, v0
	v_mov_b32_e32 v74, v0
	v_mov_b32_e32 v75, v0
	v_mov_b32_e32 v76, v0
	v_mov_b32_e32 v77, v0
	v_mov_b32_e32 v78, v0
	v_mov_b32_e32 v79, v0
	v_mov_b32_e32 v80, v0
	v_mov_b32_e32 v81, v0
	v_mov_b32_e32 v82, v0
	v_mov_b32_e32 v83, v0
	v_mov_b32_e32 v84, v0
	v_mov_b32_e32 v85, v0
	v_mov_b32_e32 v86, v0
	v_mov_b32_e32 v87, v0
	v_mov_b32_e32 v88, v0
	v_mov_b32_e32 v89, v0
	v_mov_b32_e32 v90, v0
	v_mov_b32_e32 v91, v0
	v_mov_b32_e32 v92, v0
	v_mov_b32_e32 v93, v0
	v_mov_b32_e32 v94, v0
	v_mov_b32_e32 v95, v0
	v_mov_b32_e32 v96, v0
	v_mov_b32_e32 v97, v0
	v_mov_b32_e32 v98, v0
	v_mov_b32_e32 v99, v0
	v_mov_b32_e32 v100, v0
	v_mov_b32_e32 v101, v0
	v_mov_b32_e32 v102, v0
	v_mov_b32_e32 v103, v0
	v_mov_b32_e32 v104, v0
	v_mov_b32_e32 v105, v0
	v_mov_b32_e32 v106, v0
	v_mov_b32_e32 v107, v0
	v_mov_b32_e32 v108, v0
	v_mov_b32_e32 v109, v0
	v_mov_b32_e32 v110, v0
	v_mov_b32_e32 v111, v0
	v_mov_b32_e32 v112, v0
	v_mov_b32_e32 v113, v0
	v_mov_b32_e32 v114, v0
	v_mov_b32_e32 v115, v0
	v_mov_b32_e32 v116, v0
	v_mov_b32_e32 v117, v0
	v_mov_b32_e32 v118, v0
	v_mov_b32_e32 v119, v0
	v_mov_b32_e32 v120, v0
	v_mov_b32_e32 v121, v0
	v_mov_b32_e32 v122, v0
	v_mov_b32_e32 v123, v0
	v_mov_b32_e32 v124, v0
	v_mov_b32_e32 v125, v0
	v_mov_b32_e32 v126, v0
	v_mov_b32_e32 v127, v0
	s_waitcnt lgkmcnt(0)
	s_barrier
	v_add_u32_e32 v246, s94, v184
	s_lshl_b64 s[100:101], s[94:95], 2
	v_add_u32_e32 v247, s94, v246
	s_add_u32 s100, s4, s100
	s_addc_u32 s101, s5, s101
	v_add_u32_e32 v248, s94, v247
	ds_read_b128 v[194:197], v140 offset:36864
	ds_read_b128 v[218:221], v140 offset:41472
	ds_read_b128 v[222:225], v139
	ds_read_b128 v[226:229], v139 offset:4608
	ds_read_b128 v[230:233], v139 offset:9216
; #define MFMA(a, b, c) __builtin_amdgcn_mfma_f32_32x32x16_bf16((a), (b), (c), 0, 0, 0)
; template <bool SWAP, bool SSQ, class AF>
; DI void gemm_main(AF asrc, int m0, const u16* __restrict__ Bw, int ldb, int K, char* smem,
;                   f32x16 (&acc)[4][2], float ssq_eps, float (&rs)[4]) {
;     ...
;   for (int kt = 0; kt < nkt; ++kt) {
;     if (kt + 1 < nkt) gload(kt + 1);
;     __builtin_amdgcn_sched_barrier(0);
;     {
;       bf16x8 ar[3], br[2][2];
;       ar[0] = *(const bf16x8*)(pA);
;       ar[1] = *(const bf16x8*)(pA + 32 * 144);
;       br[0][0] = *(const bf16x8*)(pB);
;       br[0][1] = *(const bf16x8*)(pB + 32 * 144);
;       __builtin_amdgcn_sched_group_barrier(0x100, 4, 0);
; #pragma unroll
;       for (int t = 0; t < 16; ++t) {
;         const int ks = t >> 2, mi = t & 3;
;         if (t + 2 < 16) {
;           ar[(t + 2) % 3] = *(const bf16x8*)(pA + ((t + 2) & 3) * (32 * 144) + ((t + 2) >> 2) * 32);
;           if (mi == 1 && ks + 1 < 4) {
;             br[(ks + 1) & 1][0] = *(const bf16x8*)(pB + (ks + 1) * 32);
;             br[(ks + 1) & 1][1] = *(const bf16x8*)(pB + 32 * 144 + (ks + 1) * 32);
;             __builtin_amdgcn_sched_group_barrier(0x100, 3, 0);
;           } else {
;             __builtin_amdgcn_sched_group_barrier(0x100, 1, 0);
;           }
;         }
;         acc[mi][0] = SWAP ? MFMA(br[ks & 1][0], ar[t % 3], acc[mi][0]) : MFMA(ar[t % 3], br[ks & 1][0], acc[mi][0]);
;         acc[mi][1] = SWAP ? MFMA(br[ks & 1][1], ar[t % 3], acc[mi][1]) : MFMA(ar[t % 3], br[ks & 1][1], acc[mi][1]);
;         __builtin_amdgcn_sched_group_barrier(0x008, 2, 0);
;         if (SSQ) {
;           u32x4 u = __builtin_bit_cast(u32x4, ar[t % 3]);
; #pragma unroll
;           for (int j = 0; j < 4; ++j) rs[mi] = dot2bf(u[j], rs[mi]);
;         }
;       }
;     }
;     __syncthreads();
;     if (kt + 1 < nkt) sstore();
;     __syncthreads();
;   }
.LBB0_354:
	ds_read_b128 v[234:237], v139 offset:13824
	global_load_dwordx4 v[144:147], v184, s[4:5]
	global_load_dwordx4 v[148:151], v246, s[4:5]
	s_waitcnt lgkmcnt(3)
	v_mfma_f32_32x32x16_bf16 v[112:127], v[194:197], v[222:225], v[112:127]
	v_mfma_f32_32x32x16_bf16 v[96:111], v[218:221], v[222:225], v[96:111]
	ds_read_b128 v[222:225], v140 offset:36896
	ds_read_b128 v[238:241], v140 offset:41504
	global_load_dwordx4 v[152:155], v247, s[4:5]
	global_load_dwordx4 v[156:159], v248, s[4:5]
	s_waitcnt lgkmcnt(4)
	v_mfma_f32_32x32x16_bf16 v[80:95], v[194:197], v[226:229], v[80:95]
	v_mfma_f32_32x32x16_bf16 v[64:79], v[218:221], v[226:229], v[64:79]
	ds_read_b128 v[226:229], v139 offset:32
	global_load_dwordx4 v[160:163], v184, s[100:101]
	global_load_dwordx4 v[164:167], v246, s[100:101]
	s_waitcnt lgkmcnt(4)
	v_mfma_f32_32x32x16_bf16 v[48:63], v[194:197], v[230:233], v[48:63]
	v_mfma_f32_32x32x16_bf16 v[32:47], v[218:221], v[230:233], v[32:47]
	ds_read_b128 v[230:233], v139 offset:4640
	global_load_dwordx4 v[168:171], v247, s[100:101]
	global_load_dwordx4 v[172:175], v248, s[100:101]
	s_waitcnt lgkmcnt(4)
	v_mfma_f32_32x32x16_bf16 v[16:31], v[194:197], v[234:237], v[16:31]
	v_mfma_f32_32x32x16_bf16 v[0:15], v[218:221], v[234:237], v[0:15]
	ds_read_b128 v[194:197], v139 offset:9248
	ds_read_b128 v[218:221], v139 offset:13856
	global_load_dwordx4 v[176:179], v184, s[96:97]
	global_load_dwordx4 v[180:183], v184, s[86:87]
	s_waitcnt lgkmcnt(3)
	v_mfma_f32_32x32x16_bf16 v[112:127], v[222:225], v[226:229], v[112:127]
	v_mfma_f32_32x32x16_bf16 v[96:111], v[238:241], v[226:229], v[96:111]
	ds_read_b128 v[226:229], v140 offset:36928
	ds_read_b128 v[202:205], v140 offset:41536
	global_load_dwordx4 v[186:189], v184, vcc
	global_load_dwordx4 v[190:193], v184, s[10:11]
	s_waitcnt lgkmcnt(4)
	v_mfma_f32_32x32x16_bf16 v[80:95], v[222:225], v[230:233], v[80:95]
	v_mfma_f32_32x32x16_bf16 v[64:79], v[238:241], v[230:233], v[64:79]
	ds_read_b128 v[230:233], v139 offset:64
	ds_read_b128 v[206:209], v139 offset:4672
	s_waitcnt lgkmcnt(5)
	v_mfma_f32_32x32x16_bf16 v[48:63], v[222:225], v[194:197], v[48:63]
	v_mfma_f32_32x32x16_bf16 v[32:47], v[238:241], v[194:197], v[32:47]
	ds_read_b128 v[194:197], v139 offset:9280
	s_waitcnt lgkmcnt(5)
	v_mfma_f32_32x32x16_bf16 v[16:31], v[222:225], v[218:221], v[16:31]
	v_mfma_f32_32x32x16_bf16 v[0:15], v[238:241], v[218:221], v[0:15]
	ds_read_b128 v[222:225], v139 offset:13888
	ds_read_b128 v[242:245], v140 offset:36960
	ds_read_b128 v[234:237], v140 offset:41568
	s_waitcnt lgkmcnt(5)
	v_mfma_f32_32x32x16_bf16 v[112:127], v[226:229], v[230:233], v[112:127]
	v_mfma_f32_32x32x16_bf16 v[96:111], v[202:205], v[230:233], v[96:111]
	ds_read_b128 v[218:221], v139 offset:96
	ds_read_b128 v[230:233], v139 offset:4704
	s_waitcnt lgkmcnt(6)
	v_mfma_f32_32x32x16_bf16 v[80:95], v[226:229], v[206:209], v[80:95]
	v_mfma_f32_32x32x16_bf16 v[64:79], v[202:205], v[206:209], v[64:79]
	ds_read_b128 v[238:241], v139 offset:9312
	ds_read_b128 v[206:209], v139 offset:13920
	s_waitcnt lgkmcnt(0)
	s_barrier
	v_mfma_f32_32x32x16_bf16 v[48:63], v[226:229], v[194:197], v[48:63]
	v_mfma_f32_32x32x16_bf16 v[32:47], v[202:205], v[194:197], v[32:47]
	s_waitcnt vmcnt(11)
	ds_write_b128 v138, v[144:147]
	s_waitcnt vmcnt(10)
	ds_write_b128 v138, v[148:151] offset:4608
	s_waitcnt vmcnt(9)
	ds_write_b128 v138, v[152:155] offset:9216
	s_waitcnt vmcnt(8)
	ds_write_b128 v138, v[156:159] offset:13824
	v_mfma_f32_32x32x16_bf16 v[16:31], v[226:229], v[222:225], v[16:31]
	v_mfma_f32_32x32x16_bf16 v[0:15], v[202:205], v[222:225], v[0:15]
	s_waitcnt vmcnt(7)
	ds_write_b128 v138, v[160:163] offset:18432
	s_waitcnt vmcnt(6)
	ds_write_b128 v138, v[164:167] offset:23040
	s_waitcnt vmcnt(5)
	ds_write_b128 v138, v[168:171] offset:27648
	s_waitcnt vmcnt(4)
	ds_write_b128 v138, v[172:175] offset:32256
	v_mfma_f32_32x32x16_bf16 v[112:127], v[242:245], v[218:221], v[112:127]
	v_mfma_f32_32x32x16_bf16 v[96:111], v[234:237], v[218:221], v[96:111]
	s_waitcnt vmcnt(3)
	ds_write_b128 v138, v[176:179] offset:36864
	s_waitcnt vmcnt(2)
	ds_write_b128 v138, v[180:183] offset:41472
	s_waitcnt vmcnt(1)
	ds_write_b128 v138, v[186:189] offset:46080
	s_waitcnt vmcnt(0)
	ds_write_b128 v138, v[190:193] offset:50688
	v_mfma_f32_32x32x16_bf16 v[80:95], v[242:245], v[230:233], v[80:95]
	v_mfma_f32_32x32x16_bf16 v[64:79], v[234:237], v[230:233], v[64:79]
	s_waitcnt lgkmcnt(0)
	s_barrier
	ds_read_b128 v[194:197], v140 offset:36864
	ds_read_b128 v[218:221], v140 offset:41472
	ds_read_b128 v[222:225], v139
	ds_read_b128 v[226:229], v139 offset:4608
	ds_read_b128 v[230:233], v139 offset:9216
	v_mfma_f32_32x32x16_bf16 v[48:63], v[242:245], v[238:241], v[48:63]
	v_mfma_f32_32x32x16_bf16 v[32:47], v[234:237], v[238:241], v[32:47]
	v_mfma_f32_32x32x16_bf16 v[16:31], v[242:245], v[206:209], v[16:31]
	v_mfma_f32_32x32x16_bf16 v[0:15], v[234:237], v[206:209], v[0:15]
	s_add_u32 s96, s96, 0x80
	s_addc_u32 s97, s97, 0
	s_add_u32 vcc_lo, vcc_lo, 0x80
	s_addc_u32 vcc_hi, vcc_hi, 0
	s_add_u32 s10, s10, 0x80
	s_addc_u32 s11, s11, 0
	s_add_u32 s86, s86, 0x80
	s_addc_u32 s87, s87, 0
	s_add_u32 s4, s4, 0x80
	s_addc_u32 s5, s5, 0
	s_add_u32 s100, s100, 0x80
	s_addc_u32 s101, s101, 0
	s_add_i32 s89, s89, -1
	s_cmp_lg_u32 s89, 0
	s_cbranch_scc1 .LBB0_354
; #define MFMA(a, b, c) __builtin_amdgcn_mfma_f32_32x32x16_bf16((a), (b), (c), 0, 0, 0)
; template <bool SWAP, bool SSQ, class AF>
; DI void gemm_main(AF asrc, int m0, const u16* __restrict__ Bw, int ldb, int K, char* smem,
;                   f32x16 (&acc)[4][2], float ssq_eps, float (&rs)[4]) {
;     ...
;   for (int kt = 0; kt < nkt; ++kt) {
;     if (kt + 1 < nkt) gload(kt + 1);
;     __builtin_amdgcn_sched_barrier(0);
;     {
;       bf16x8 ar[3], br[2][2];
;       ar[0] = *(const bf16x8*)(pA);
;       ar[1] = *(const bf16x8*)(pA + 32 * 144);
;       br[0][0] = *(const bf16x8*)(pB);
;       br[0][1] = *(const bf16x8*)(pB + 32 * 144);
;       __builtin_amdgcn_sched_group_barrier(0x100, 4, 0);
; #pragma unroll
;       for (int t = 0; t < 16; ++t) {
;         const int ks = t >> 2, mi = t & 3;
;         if (t + 2 < 16) {
;           ar[(t + 2) % 3] = *(const bf16x8*)(pA + ((t + 2) & 3) * (32 * 144) + ((t + 2) >> 2) * 32);
;           if (mi == 1 && ks + 1 < 4) {
;             br[(ks + 1) & 1][0] = *(const bf16x8*)(pB + (ks + 1) * 32);
;             br[(ks + 1) & 1][1] = *(const bf16x8*)(pB + 32 * 144 + (ks + 1) * 32);
;             __builtin_amdgcn_sched_group_barrier(0x100, 3, 0);
;           } else {
;             __builtin_amdgcn_sched_group_barrier(0x100, 1, 0);
;           }
;         }
;         acc[mi][0] = SWAP ? MFMA(br[ks & 1][0], ar[t % 3], acc[mi][0]) : MFMA(ar[t % 3], br[ks & 1][0], acc[mi][0]);
;         acc[mi][1] = SWAP ? MFMA(br[ks & 1][1], ar[t % 3], acc[mi][1]) : MFMA(ar[t % 3], br[ks & 1][1], acc[mi][1]);
;         __builtin_amdgcn_sched_group_barrier(0x008, 2, 0);
;         if (SSQ) {
;           u32x4 u = __builtin_bit_cast(u32x4, ar[t % 3]);
; #pragma unroll
;           for (int j = 0; j < 4; ++j) rs[mi] = dot2bf(u[j], rs[mi]);
;         }
;       }
;     }
;     __syncthreads();
;     if (kt + 1 < nkt) sstore();
;     __syncthreads();
;   }
; DI void phase_upproj(const Params& p, const GroupP& g, int l, char* smem, int vb) {
;     ...
;       {
;         const float* sq = p.rowsq + (size_t)(l * 2 + (isq ? 0 : 1)) * 50432 + g.seq0 + m0 + wm * 128 + lr;
;         const float invK = 1.f / (float)Kd;
; #pragma unroll
;         for (int mi = 0; mi < 4; ++mi) rs[mi] = __builtin_amdgcn_rsqf(sq[mi * 32] * invK + 1e-6f);
;       }
	ds_read_b128 v[144:147], v140 offset:36864
	ds_read_b128 v[156:159], v140 offset:41472
	ds_read_b128 v[148:151], v139
	ds_read_b128 v[152:155], v139 offset:4608
	ds_read_b128 v[160:163], v139 offset:9216
	v_cndmask_b32_e64 v138, 0, 1, s[92:93]
	v_or_b32_e32 v138, s41, v138
	s_mov_b32 s4, 0x31400
	v_mul_lo_u32 v184, v138, s4
	s_waitcnt lgkmcnt(2)
	v_mfma_f32_32x32x16_bf16 v[112:127], v[144:147], v[148:151], v[112:127]
	v_readlane_b32 s4, v253, 7
	v_readlane_b32 s5, v253, 8
	v_cvt_f32_u32_e32 v142, s21
	v_readlane_b32 s6, v254, 36
	s_mov_b32 s87, s40
	v_readlane_b32 s7, v254, 37
	v_mfma_f32_32x32x16_bf16 v[96:111], v[156:159], v[148:151], v[96:111]
	ds_read_b128 v[164:167], v140 offset:36896
	ds_read_b128 v[168:171], v140 offset:41504
	ds_read_b128 v[148:151], v139 offset:13824
	s_waitcnt lgkmcnt(4)
	v_mfma_f32_32x32x16_bf16 v[80:95], v[144:147], v[152:155], v[80:95]
	v_mfma_f32_32x32x16_bf16 v[64:79], v[156:159], v[152:155], v[64:79]
	ds_read_b128 v[152:155], v139 offset:32
	s_waitcnt lgkmcnt(4)
	v_mfma_f32_32x32x16_bf16 v[48:63], v[144:147], v[160:163], v[48:63]
	v_mfma_f32_32x32x16_bf16 v[32:47], v[156:159], v[160:163], v[32:47]
	ds_read_b128 v[160:163], v139 offset:4640
	s_waitcnt lgkmcnt(2)
	v_mfma_f32_32x32x16_bf16 v[16:31], v[144:147], v[148:151], v[16:31]
	v_mfma_f32_32x32x16_bf16 v[0:15], v[156:159], v[148:151], v[0:15]
	ds_read_b128 v[144:147], v139 offset:9248
	s_waitcnt lgkmcnt(2)
	v_mfma_f32_32x32x16_bf16 v[112:127], v[164:167], v[152:155], v[112:127]
	v_mfma_f32_32x32x16_bf16 v[96:111], v[168:171], v[152:155], v[96:111]
	ds_read_b128 v[152:155], v140 offset:36928
	ds_read_b128 v[156:159], v140 offset:41536
	ds_read_b128 v[148:151], v139 offset:13856
	s_waitcnt lgkmcnt(4)
	v_mfma_f32_32x32x16_bf16 v[80:95], v[164:167], v[160:163], v[80:95]
	v_mfma_f32_32x32x16_bf16 v[64:79], v[168:171], v[160:163], v[64:79]
	ds_read_b128 v[160:163], v139 offset:64
	s_waitcnt lgkmcnt(4)
	v_mfma_f32_32x32x16_bf16 v[48:63], v[164:167], v[144:147], v[48:63]
	v_mfma_f32_32x32x16_bf16 v[32:47], v[168:171], v[144:147], v[32:47]
	ds_read_b128 v[144:147], v139 offset:4672
	s_waitcnt lgkmcnt(2)
	v_mfma_f32_32x32x16_bf16 v[16:31], v[164:167], v[148:151], v[16:31]
	v_mfma_f32_32x32x16_bf16 v[0:15], v[168:171], v[148:151], v[0:15]
	ds_read_b128 v[148:151], v139 offset:9280
	s_waitcnt lgkmcnt(2)
	v_mfma_f32_32x32x16_bf16 v[112:127], v[152:155], v[160:163], v[112:127]
	v_mfma_f32_32x32x16_bf16 v[96:111], v[156:159], v[160:163], v[96:111]
	ds_read_b128 v[164:167], v140 offset:36960
	ds_read_b128 v[168:171], v140 offset:41568
	ds_read_b128 v[160:163], v139 offset:13888
	s_waitcnt lgkmcnt(4)
	v_mfma_f32_32x32x16_bf16 v[80:95], v[152:155], v[144:147], v[80:95]
	v_mfma_f32_32x32x16_bf16 v[64:79], v[156:159], v[144:147], v[64:79]
	ds_read_b128 v[144:147], v139 offset:96
	s_waitcnt lgkmcnt(4)
	v_mfma_f32_32x32x16_bf16 v[48:63], v[152:155], v[148:151], v[48:63]
	v_mfma_f32_32x32x16_bf16 v[32:47], v[156:159], v[148:151], v[32:47]
	ds_read_b128 v[148:151], v139 offset:4704
	s_waitcnt lgkmcnt(2)
	v_mfma_f32_32x32x16_bf16 v[16:31], v[152:155], v[160:163], v[16:31]
	v_mfma_f32_32x32x16_bf16 v[0:15], v[156:159], v[160:163], v[0:15]
	ds_read_b128 v[152:155], v139 offset:9312
	s_waitcnt lgkmcnt(2)
	v_mfma_f32_32x32x16_bf16 v[112:127], v[164:167], v[144:147], v[112:127]
	v_mfma_f32_32x32x16_bf16 v[96:111], v[168:171], v[144:147], v[96:111]
	ds_read_b128 v[144:147], v139 offset:13920
	v_lshl_add_u64 v[138:139], s[4:5], 0, v[184:185]
	s_lshl_b64 s[4:5], s[90:91], 2
	v_lshl_add_u64 v[138:139], v[138:139], 0, s[4:5]
	v_readlane_b32 s4, v254, 41
	v_readlane_b32 s5, v254, 42
	s_waitcnt lgkmcnt(0)
	s_barrier
	v_lshl_add_u64 v[138:139], v[138:139], 0, s[4:5]
	s_nop 0
	v_readfirstlane_b32 s4, v138
	v_readfirstlane_b32 s5, v139
	s_barrier
; DI void phase_upproj(const Params& p, const GroupP& g, int l, char* smem, int vb) {
;     ...
;       {
;         const float* sq = p.rowsq + (size_t)(l * 2 + (isq ? 0 : 1)) * 50432 + g.seq0 + m0 + wm * 128 + lr;
;         const float invK = 1.f / (float)Kd;
; #pragma unroll
;         for (int mi = 0; mi < 4; ++mi) rs[mi] = __builtin_amdgcn_rsqf(sq[mi * 32] * invK + 1e-6f);
;       }
;       const int nw0 = n0 + wn * 64;
;       if (isq) {
;         const int head = nw0 / 192, w = nw0 - head * 192;
; #pragma unroll
;         for (int mi = 0; mi < 4; ++mi) {
;           int m = m0 + wm * 128 + mi * 32 + lr;
;           float r = rs[mi];
;           if (w == 128) {
;             int b = m / g.Lp, t = m - b * g.Lp;
;             f32x16 a0 = acc[mi][0], a1 = acc[mi][1];
; #pragma unroll
;             for (int i = 0; i < 16; ++i) { a0[i] *= r; a1[i] *= r; }
;             rope_store(a0, a1, p.rope + t * 32, g.q + (long)m * 1536 + nw0, lh);
;           } else {
;             u16* qp = g.q + (long)m * 1536 + nw0;
; #pragma unroll
;             for (int ni = 0; ni < 2; ++ni)
; #pragma unroll
;               for (int pr = 0; pr < 2; ++pr)
;                 store_bf8_pair(qp + ni * 32 + 16 * pr, lh, acc[mi][ni][8 * pr] * r, acc[mi][ni][8 * pr + 1] * r,
;                                acc[mi][ni][8 * pr + 2] * r, acc[mi][ni][8 * pr + 3] * r, acc[mi][ni][8 * pr + 4] * r,
;                                acc[mi][ni][8 * pr + 5] * r, acc[mi][ni][8 * pr + 6] * r, acc[mi][ni][8 * pr + 7] * r);
	v_mfma_f32_32x32x16_bf16 v[80:95], v[164:167], v[148:151], v[80:95]
	s_nop 2
	global_load_dword v138, v143, s[4:5]
	global_load_dword v139, v143, s[4:5] offset:128
	global_load_dword v140, v143, s[4:5] offset:256
	v_mfma_f32_32x32x16_bf16 v[64:79], v[168:171], v[148:151], v[64:79]
	global_load_dword v148, v143, s[4:5] offset:384
	v_div_scale_f32 v149, s[4:5], v142, v142, 1.0
	v_rcp_f32_e32 v150, v149
	s_mov_b64 s[4:5], -1
	v_mfma_f32_32x32x16_bf16 v[48:63], v[164:167], v[152:155], v[48:63]
	v_mfma_f32_32x32x16_bf16 v[32:47], v[168:171], v[152:155], v[32:47]
	v_mfma_f32_32x32x16_bf16 v[16:31], v[164:167], v[144:147], v[16:31]
	v_mfma_f32_32x32x16_bf16 v[0:15], v[168:171], v[144:147], v[0:15]
	v_fma_f32 v144, -v149, v150, 1.0
	v_fmac_f32_e32 v150, v144, v150
	v_div_scale_f32 v144, vcc, 1.0, v142, 1.0
	v_mul_f32_e32 v145, v144, v150
	v_fma_f32 v146, -v149, v145, v144
	v_fmac_f32_e32 v145, v146, v150
	v_fma_f32 v144, -v149, v145, v144
	v_div_fmas_f32 v144, v144, v150, v145
	v_div_fixup_f32 v145, v144, v142, 1.0
	v_add_u32_e32 v146, s90, v129
	s_andn2_b64 vcc, exec, s[8:9]
	s_waitcnt vmcnt(3)
	v_fmaak_f32 v138, v145, v138, 0x358637bd
	v_rsq_f32_e32 v144, v138
	s_waitcnt vmcnt(2)
	v_fmaak_f32 v138, v145, v139, 0x358637bd
	v_rsq_f32_e32 v142, v138
	s_waitcnt vmcnt(1)
	v_fmaak_f32 v138, v145, v140, 0x358637bd
	v_rsq_f32_e32 v140, v138
	s_waitcnt vmcnt(0)
	v_fmaak_f32 v138, v145, v148, 0x358637bd
	v_rsq_f32_e32 v138, v138
	s_cbranch_vccnz .LBB0_368
	s_or_b32 s90, s20, s16
	s_mul_hi_i32 s4, s90, 0x2aaaaaab
	s_lshr_b32 s5, s4, 31
	s_lshr_b32 s4, s4, 5
	s_add_i32 s4, s4, s5
	s_mulk_i32 s4, 0xc0
	s_sub_i32 s4, s90, s4
	s_cmpk_lg_i32 s4, 0x80
	s_cselect_b64 s[4:5], -1, 0
	s_ashr_i32 s91, s90, 31
	s_mov_b64 s[6:7], -1
	s_and_b64 vcc, exec, s[4:5]
	v_lshlrev_b32_e32 v184, 1, v130
	s_cbranch_vccz .LBB0_358
	v_readlane_b32 s44, v253, 47
	v_readlane_b32 s46, v253, 49
	v_readlane_b32 s47, v253, 50
	s_movk_i32 s6, 0xc00
	v_pk_mul_f32 v[150:151], v[114:115], v[144:145] op_sel_hi:[1,0]
	v_mov_b64_e32 v[148:149], s[46:47]
	v_mad_i64_i32 v[148:149], s[6:7], v146, s6, v[148:149]
	v_lshl_add_u64 v[148:149], s[90:91], 1, v[148:149]
	v_lshl_add_u64 v[152:153], v[148:149], 0, v[184:185]
	v_pk_mul_f32 v[148:149], v[112:113], v[144:145] op_sel_hi:[1,0]
	v_pk_mul_f32 v[154:155], v[116:117], v[144:145] op_sel_hi:[1,0]
	v_pk_mul_f32 v[156:157], v[118:119], v[144:145] op_sel_hi:[1,0]
	v_cvt_pk_bf16_f32 v148, v148, v149
	v_cvt_pk_bf16_f32 v149, v150, v151
	v_cvt_pk_bf16_f32 v150, v154, v155
	v_cvt_pk_bf16_f32 v151, v156, v157
	s_nop 0
	v_permlane32_swap_b32_e32 v148, v150
	v_permlane32_swap_b32_e32 v149, v151
	global_store_dwordx4 v[152:153], v[148:151], off
	v_pk_mul_f32 v[154:155], v[124:125], v[144:145] op_sel_hi:[1,0]
	v_pk_mul_f32 v[156:157], v[126:127], v[144:145] op_sel_hi:[1,0]
	v_pk_mul_f32 v[148:149], v[120:121], v[144:145] op_sel_hi:[1,0]
	v_pk_mul_f32 v[150:151], v[122:123], v[144:145] op_sel_hi:[1,0]
	v_cvt_pk_bf16_f32 v148, v148, v149
	v_cvt_pk_bf16_f32 v149, v150, v151
	v_cvt_pk_bf16_f32 v150, v154, v155
	v_cvt_pk_bf16_f32 v151, v156, v157
	s_nop 0
	v_permlane32_swap_b32_e32 v148, v150
	v_permlane32_swap_b32_e32 v149, v151
	global_store_dwordx4 v[152:153], v[148:151], off offset:32
	v_pk_mul_f32 v[154:155], v[100:101], v[144:145] op_sel_hi:[1,0]
	v_pk_mul_f32 v[156:157], v[102:103], v[144:145] op_sel_hi:[1,0]
	v_pk_mul_f32 v[148:149], v[96:97], v[144:145] op_sel_hi:[1,0]
	v_pk_mul_f32 v[150:151], v[98:99], v[144:145] op_sel_hi:[1,0]
	v_cvt_pk_bf16_f32 v148, v148, v149
	v_cvt_pk_bf16_f32 v149, v150, v151
	v_cvt_pk_bf16_f32 v150, v154, v155
	v_cvt_pk_bf16_f32 v151, v156, v157
	s_nop 0
	v_permlane32_swap_b32_e32 v148, v150
	v_permlane32_swap_b32_e32 v149, v151
	global_store_dwordx4 v[152:153], v[148:151], off offset:64
	v_pk_mul_f32 v[154:155], v[108:109], v[144:145] op_sel_hi:[1,0]
	v_pk_mul_f32 v[156:157], v[110:111], v[144:145] op_sel_hi:[1,0]
	v_pk_mul_f32 v[148:149], v[104:105], v[144:145] op_sel_hi:[1,0]
	v_pk_mul_f32 v[150:151], v[106:107], v[144:145] op_sel_hi:[1,0]
	v_cvt_pk_bf16_f32 v148, v148, v149
	v_cvt_pk_bf16_f32 v149, v150, v151
	v_cvt_pk_bf16_f32 v150, v154, v155
	v_cvt_pk_bf16_f32 v151, v156, v157
	s_nop 0
	v_permlane32_swap_b32_e32 v148, v150
	v_permlane32_swap_b32_e32 v149, v151
	v_readlane_b32 s45, v253, 48
	v_readlane_b32 s48, v253, 51
	v_readlane_b32 s49, v253, 52
	v_readlane_b32 s50, v253, 53
	v_readlane_b32 s51, v253, 54
	global_store_dwordx4 v[152:153], v[148:151], off offset:96
	s_mov_b64 s[6:7], 0
